# v22: v4 plus one static s_setprio 1 for waves 4-7 during the prompt recurrence items (restored at item end)
# speedup vs baseline: 1.0002x; 1.0002x over previous
.LBB0_353:
	s_setprio 0
	s_ashr_i32 s71, s70, 31
	v_or_b32_e32 v0, s57, v113
	s_lshl_b64 s[0:1], s[70:71], 16
	v_ashrrev_i32_e32 v1, 31, v0
	s_add_u32 s0, s77, s0
	v_lshlrev_b64 v[4:5], 9, v[0:1]
	v_or_b32_e32 v6, 1, v0
	v_or_b32_e32 v8, 2, v0
	v_or_b32_e32 v0, 3, v0
	s_addc_u32 s1, s80, s1
	v_lshlrev_b32_e32 v96, 2, v107
	v_ashrrev_i32_e32 v7, 31, v6
	v_ashrrev_i32_e32 v9, 31, v8
	v_ashrrev_i32_e32 v1, 31, v0
	v_lshl_add_u64 v[2:3], s[0:1], 0, v[96:97]
	v_lshlrev_b64 v[6:7], 9, v[6:7]
	v_lshlrev_b64 v[8:9], 9, v[8:9]
	v_lshlrev_b64 v[0:1], 9, v[0:1]
	v_lshl_add_u64 v[4:5], v[2:3], 0, v[4:5]
	v_lshl_add_u64 v[6:7], v[2:3], 0, v[6:7]
	v_lshl_add_u64 v[8:9], v[2:3], 0, v[8:9]
	v_lshl_add_u64 v[0:1], v[2:3], 0, v[0:1]
	global_store_dword v[4:5], v24, off
	global_store_dword v[6:7], v25, off
	global_store_dword v[8:9], v26, off
	global_store_dword v[0:1], v27, off
	global_store_dword v[4:5], v32, off offset:64
	global_store_dword v[6:7], v33, off offset:64
	global_store_dword v[8:9], v34, off offset:64
	global_store_dword v[0:1], v35, off offset:64
	global_store_dword v[4:5], v40, off offset:128
	global_store_dword v[6:7], v41, off offset:128
	global_store_dword v[8:9], v42, off offset:128
	global_store_dword v[0:1], v43, off offset:128
	global_store_dword v[4:5], v44, off offset:192
	global_store_dword v[6:7], v45, off offset:192
	global_store_dword v[8:9], v46, off offset:192
	global_store_dword v[0:1], v47, off offset:192
	global_store_dword v[4:5], v28, off offset:256
	global_store_dword v[6:7], v29, off offset:256
	global_store_dword v[8:9], v30, off offset:256
	global_store_dword v[0:1], v31, off offset:256
	global_store_dword v[4:5], v36, off offset:320
	global_store_dword v[6:7], v37, off offset:320
	global_store_dword v[8:9], v38, off offset:320
	global_store_dword v[0:1], v39, off offset:320
	global_store_dword v[4:5], v48, off offset:384
	global_store_dword v[6:7], v49, off offset:384
	global_store_dword v[8:9], v50, off offset:384
	global_store_dword v[0:1], v51, off offset:384
	global_store_dword v[4:5], v52, off offset:448
	global_store_dword v[6:7], v53, off offset:448
	global_store_dword v[8:9], v54, off offset:448
	global_store_dword v[0:1], v55, off offset:448
	s_waitcnt lgkmcnt(0)
	s_barrier

.LBB0_469:
	s_and_b64 vcc, exec, s[0:1]
	s_cbranch_vccz .LBB0_354
	v_readfirstlane_b32 s99, v208
	s_lshr_b32 s99, s99, 6
	s_cmp_lt_u32 s99, 4
	s_cbranch_scc1 .Lpr_skip
	s_setprio 1
.Lpr_skip:
	v_mov_b32_e32 v253, 0x3800
	v_readfirstlane_b32 s99, v208
	s_lshr_b32 s99, s99, 6
	s_cmp_lg_u32 s99, 0
	s_cbranch_scc1 .Lspin_join_g0
	s_mov_b32 s99, 0
